# prep re-deal v2: workgroups with mod/ssm first jobs take no transposes in phase 0 and in the branch-phase part
# baseline (speedup 1.0000x reference)
; __device__ __forceinline__ void prep_layer_jobs(PP p, unsigned char* smem, int layer, int start, int stride, int jlo, int jhi) {
;     for (int j = jlo + start; j < jhi; j += stride) {
;         if (j < 48) job_mod(p, smem, layer * 48 + j);
;         else if (j < 80) job_ssm(p, smem, layer * 32 + (j - 48));
;         else if (j < 208) job_fold(p, smem, layer * 128 + (j - 80));
;         else if (j < 2000) { const int rem = j - 208, rt = rem / 56, ct = rem % 56; if (ct == 8 || ct == 9) continue;
;             transpose_tile(p->w_in + (size_t)layer * DM * NIN, NIN, rt * 64, ct * 256, (bf16_t*)(p->ws + WS_WINT) + (size_t)layer * NIN * DM, DM, 2, smem); }
;         else if (j < 2256) { const int rem = j - 2000, rt = rem >> 3, ct = rem & 7;
;             transpose_tile(p->w_br + (size_t)layer * DM * DM, DM, rt * 64, ct * 256, (bf16_t*)(p->ws + WS_WBRT) + (size_t)layer * DM * DM, DM, 0, smem); }
;         else if (j < 2512) { const int rem = j - 2256, rt = rem >> 3, ct = rem & 7;
;             transpose_tile(p->w_o + (size_t)layer * DM * DM, DM, rt * 64, ct * 256, (bf16_t*)(p->ws + WS_WOT) + (size_t)layer * DM * DM, DM, 0, smem); }
;         else { const int rem = j - 2512, rt = rem >> 2, ct = rem & 3;
;             transpose_tile(p->glu_w + (size_t)layer * 512 * 1024, 1024, rt * 64, ct * 256, (bf16_t*)(p->ws + WS_GLUT) + (size_t)layer * 1024 * 512, 512, 1, smem); }
;     }
; }
; template <int PMASK> __device__ __forceinline__ void run_phase(PP p, int ph, unsigned char* smem) {
;     ...
;         if (layer < 3 && c >= 32) { __syncthreads(); prep_layer_jobs(p, smem, layer + 1, c - 32, G - 32, 0, 2544); } } break;
.LBB0_138:
	s_mov_b32 s4, s10
	v_writelane_b32 v249, s4, 63
	s_cmp_gt_i32 s10, 2
	v_readlane_b32 s8, v249, 11
	v_readlane_b32 s9, v249, 12
	s_cselect_b64 s[6:7], -1, 0
	s_xor_b64 s[8:9], s[8:9], -1
	s_or_b64 s[6:7], s[8:9], s[6:7]
	s_and_b64 vcc, exec, s[6:7]
	v_writelane_b32 v248, s5, 0
	s_cbranch_vccnz .LBB0_302
	v_readlane_b32 s6, v249, 15
	v_readlane_b32 s7, v249, 16
	s_andn2_b64 vcc, exec, s[6:7]
	s_waitcnt vmcnt(0) lgkmcnt(0)
	s_barrier
	s_cbranch_vccnz .LBB0_302
	v_readlane_b32 s6, v249, 63
	v_readlane_b32 s7, v248, 0
	s_add_i32 s6, s6, 1
	s_load_dwordx2 s[12:13], s[0:1], 0xd0
	s_ashr_i32 s7, s6, 31
	s_lshl_b64 s[8:9], s[6:7], 21
	v_writelane_b32 v248, s8, 4
	s_lshl_b64 s[16:17], s[6:7], 22
	s_lshl_b32 s47, s6, 7
	v_writelane_b32 v248, s9, 5
	s_lshl_b64 s[8:9], s[6:7], 20
	s_lshl_b32 s48, s6, 5
	s_waitcnt lgkmcnt(0)
	s_add_u32 s8, s12, s8
	s_addc_u32 s9, s13, s9
	s_add_u32 s46, s8, 0x12000000
	s_mul_hi_i32 s42, s6, 0x7000000
	s_mul_i32 s43, s6, 0x7000000
	s_mul_hi_i32 s4, s6, 0x3800000
	s_mul_i32 s10, s6, 0x3800000
	s_mul_i32 s49, s6, 48
	s_addc_u32 s8, s9, 0
	s_lshl_b64 s[6:7], s[6:7], 23
	v_writelane_b32 v248, s8, 3
	s_add_u32 s8, s12, s6
	s_addc_u32 s9, s13, s7
	s_add_u32 s8, s8, 0x10000000
	v_writelane_b32 v248, s8, 6
	s_addc_u32 s8, s9, 0
	s_add_u32 s61, s14, s6
	s_addc_u32 s62, s15, s7
	s_add_u32 s63, s12, s10
	s_addc_u32 s64, s13, s4
	s_add_u32 s18, s12, 0x15400000
	s_addc_u32 s19, s13, 0
	s_add_u32 s65, s12, 0x12400000
	s_addc_u32 s50, s13, 0
	s_add_u32 s51, s12, 0x14400000
	s_addc_u32 s55, s13, 0
	s_add_u32 s60, s12, 0x15420000
	s_addc_u32 s14, s13, 0
	v_readlane_b32 s15, v249, 14
	v_writelane_b32 v248, s8, 7
	v_readlane_b32 s4, v248, 62
	s_cmp_lg_u32 s4, 0
	s_cbranch_scc1 .Lprepb_part2_init
	s_cmpk_lt_i32 s15, 0xd0
	s_cbranch_scc1 .LBB0_142
	s_addk_i32 s15, 0x80
	s_branch .LBB0_142
.Lprepb_part2_init:
	s_addk_i32 s15, 0x430
	s_branch .Lprepb_check
.LBB0_141:
	v_readlane_b32 s4, v248, 62
	s_cmp_lg_u32 s4, 0
	s_cbranch_scc1 .Lprepb_step2
	s_cmpk_lt_i32 s15, 0xd0
	s_cbranch_scc1 .Lprepb_first_done
	s_addk_i32 s15, 0x90
	s_branch .Lprepb_check
.Lprepb_first_done:
	s_cmpk_lt_i32 s15, 0x50
	s_cbranch_scc1 .LBB0_302
	s_addk_i32 s15, 0x80
	s_branch .Lprepb_check
.Lprepb_step2:
	s_add_i32 s15, s45, s15
.Lprepb_check:
	v_readlane_b32 s4, v248, 62
	s_cmp_lg_u32 s4, 0
	s_movk_i32 s4, 0x430
	s_cselect_b32 s4, 0x9f0, s4
	s_cmp_ge_i32 s15, s4
	s_cbranch_scc1 .LBB0_302

; __device__ __forceinline__ void prep_layer_jobs(PP p, unsigned char* smem, int layer, int start, int stride, int jlo, int jhi) {
;     for (int j = jlo + start; j < jhi; j += stride) {
;         if (j < 48) job_mod(p, smem, layer * 48 + j);
;         else if (j < 80) job_ssm(p, smem, layer * 32 + (j - 48));
;         else if (j < 208) job_fold(p, smem, layer * 128 + (j - 80));
;         else if (j < 2000) { const int rem = j - 208, rt = rem / 56, ct = rem % 56; if (ct == 8 || ct == 9) continue;
; template <int PMASK> __device__ __forceinline__ void run_phase(PP p, int ph, unsigned char* smem) {
;     ...
;     if (ph == 0) { if constexpr ((PMASK >> 8) & 1) prep_layer_jobs(p, smem, 0, blockIdx.x, gridDim.x, 0, 2544); return; }
.LBB0_730:
	v_readlane_b32 s6, v249, 9
	v_readlane_b32 s7, v249, 10
	s_andn2_b64 vcc, exec, s[6:7]
	s_cbranch_vccnz .LBB0_12
	s_mov_b32 s14, s2
	s_cmpk_lt_i32 s14, 0xd0
	s_cbranch_scc1 .LBB0_733
	s_addk_i32 s14, 0x80
	s_branch .LBB0_733
.LBB0_732:
	s_cmpk_lt_i32 s14, 0xd0
	s_cbranch_scc1 .Lprep0_first_done
	s_addk_i32 s14, 0xb0
	s_branch .Lprep0_check
.Lprep0_first_done:
	s_cmpk_lt_i32 s14, 0x50
	s_cbranch_scc1 .LBB0_12
	s_addk_i32 s14, 0x80
